# unit prologues: kinf 16-lane max all-reduce via DPP permutes (diff + forgetting mixers) and the forgetting mixer's first log-forget suffix sum via DPP row shifts; stacked on the DPP butterfly version
# baseline (speedup 1.0000x reference)
; template <int MODE> ...
;     ...
;     const int tid = tid_, lane = tid & 63, wid = __builtin_amdgcn_readfirstlane(tid >> 6), r32 = lane & 31, hi = lane >> 5;
;     const int q0 = qblk * ROWS, wq0 = q0 + 32 * (MODE == 2 ? wid : MODE == 1 ? (wid & 1) : (wid & 3)), mapi = MODE == 2 ? 0 : MODE == 1 ? (wid >> 1) : (wid >> 2), heff = MODE == 1 ? h + mapi : h;
;     const float sl2w = MODE == 1 ? sl2 * (1.0f / (float)(1 << mapi)) : sl2, sink2w = MODE == 1 ? subg[heff] * LOG2E : sink2;
;     const size_t tok0 = (size_t)b * SEQ;
;     const int qcol = MODE == 0 ? h * 128 + mapi * 64 : MODE == 1 ? 1024 + heff * 64 : 1536 + h * 64;
;     const int kcol = MODE == 0 ? 512 + h * 128 : MODE == 1 ? 2560 + (h >> 2) * 64 : 2048 + h * 64;
;     const int vrow = MODE == 0 ? h * 128 : MODE == 1 ? 1024 + (h >> 2) * 64 : 512 + h * 64;
;     const int ycol = MODE == 0 ? h * 128 : MODE == 1 ? 512 + heff * 64 : 1024 + h * 64;
;     const bf16* Kg = QK + tok0 * N1A + kcol;
;     const bf16* Vg = VT + (size_t)vrow * M + tok0;
;     bf16x8 qr[4];
;     { const bf16* qp = QK + (tok0 + wq0 + r32) * N1A + qcol + hi * 8;
; #pragma unroll
;       for (int d0 = 0; d0 < 4; ++d0) qr[d0] = *(const bf16x8*)(qp + d0 * 16); }
;     float qkb = 0.f;
;     if (REV) {
; #pragma unroll
;         for (int d0 = 0; d0 < 4; ++d0) { const u32x4 w = __builtin_bit_cast(u32x4, qr[d0]);
;             qkb += fabsf(pg8::bflo(w.x)) + fabsf(pg8::bfhi(w.x)) + fabsf(pg8::bflo(w.y)) + fabsf(pg8::bfhi(w.y)) + fabsf(pg8::bflo(w.z)) + fabsf(pg8::bfhi(w.z)) + fabsf(pg8::bflo(w.w)) + fabsf(pg8::bfhi(w.w)); }
;         qkb = xhalf_sum(qkb) * kinf * 1.02f;
;     }
;     const int t_lo = MODE == 1 ? (q0 >= 128 ? (q0 - 128) / 64 : 0) : 0, t_hi = (q0 + ROWS) / 64;
;     int kgoff[NKL], kloff[NKL], vgoff[NVL], vloff[NVL];
; #pragma unroll
;     for (int i = 0; i < NKL; ++i) { const int idx = tid + 512 * i, row = idx / KCH, ch = idx % KCH; kgoff[i] = row * N1A + ch * 8; kloff[i] = row * KSTR + ch * 16; }
; #pragma unroll
; __device__ __forceinline__ void attn_phase(LAS unsigned char* lds, const Args& a, int layer, int vcu, int G) {
;     ...
;         int l15_ = threadIdx.x & 15; asm volatile("" : "+v"(l15_)); float kinf = kabs[(b * 16 + l15_) * 11 + 2 + (h >> 1)];
;         _Pragma("unroll") for (int o = 1; o < 16; o <<= 1) kinf = fmaxf(kinf, __shfl_xor(kinf, o));
.LBB0_243:
	s_or_b64 exec, exec, s[4:5]
	v_mov_b32_e32 v2, v197
	s_lshl_b32 s2, s1, 1
	s_andn2_b32 s5, 3, s1
	s_or_b32 s2, s2, -8
	v_add_u32_e32 v2, s86, v2
	s_not_b32 s1, s1
	v_ldexp_f32 v0, 1.0, s2
	v_mul_lo_u32 v2, v2, 11
	s_bfe_u32 s2, s1, 0x10001
	v_add3_u32 v2, v2, s2, 2
	v_ashrrev_i32_e32 v3, 31, v2
	v_lshl_add_u64 v[2:3], v[2:3], 2, s[88:89]
	global_load_dword v150, v[2:3], off
	s_lshl_b32 s1, s1, 5
	s_and_b32 s70, s1, 0xf80
	s_lshl_b32 s8, s5, 8
	v_mul_f32_e32 v208, 0x3fb8aa3b, v0
	v_mov_b32_e32 v2, v196
	s_nop 0
	v_readfirstlane_b32 s76, v2
	s_ashr_i32 s2, s76, 6
	s_and_b32 s84, s2, 3
	s_lshl_b32 s1, s84, 5
	s_ashr_i32 s77, s76, 8
	s_or_b32 s71, s1, s70
	s_lshl_b32 s1, s5, 7
	s_lshl_b32 s4, s77, 6
	s_add_i32 s4, s4, s1
	s_add_u32 s10, s22, s8
	v_and_b32_e32 v178, 31, v2
	s_addc_u32 s11, s26, 0
	s_or_b32 s75, s71, s87
	v_or_b32_e32 v0, s75, v178
	v_mul_u32_u24_e32 v0, 0x1600, v0
	v_bfe_u32 v5, v2, 5, 1
	s_lshl_b32 s9, s5, 23
	v_lshl_add_u64 v[6:7], s[80:81], 0, v[0:1]
	s_ashr_i32 s5, s4, 31
	v_lshl_add_u64 v[6:7], s[4:5], 1, v[6:7]
	v_lshlrev_b32_e32 v0, 4, v5
	v_lshl_add_u64 v[6:7], v[6:7], 0, v[0:1]
	global_load_dwordx4 v[98:101], v[6:7], off
	global_load_dwordx4 v[102:105], v[6:7], off offset:32
	global_load_dwordx4 v[106:109], v[6:7], off offset:64
	global_load_dwordx4 v[110:113], v[6:7], off offset:96
	s_movk_i32 s4, 0x110
	s_add_u32 s12, s3, s9
	s_addc_u32 s13, s0, 0
	s_add_i32 s14, s70, 0x80
	s_lshr_b32 s20, s14, 6
	s_add_i32 s68, s20, -1
	v_and_b32_e32 v209, 63, v2
	v_add_u32_e32 v8, 0x200, v2
	v_ashrrev_i32_e32 v4, 31, v2
	v_lshrrev_b32_e32 v4, 28, v4
	v_add_u32_e32 v4, v2, v4
	v_ashrrev_i32_e32 v7, 4, v4
	v_and_b32_e32 v4, 0xffffff0, v4
	v_sub_u32_e32 v4, v2, v4
	v_mul_lo_u32 v6, v7, s4
	v_lshl_add_u32 v4, v4, 4, v6
	v_ashrrev_i32_e32 v6, 31, v8
	v_lshrrev_b32_e32 v6, 28, v6
	v_add_u32_e32 v6, v8, v6
	v_ashrrev_i32_e32 v14, 4, v6
	v_and_b32_e32 v6, 0xffffff0, v6
	v_lshlrev_b32_e32 v3, 4, v2
	v_sub_u32_e32 v6, v8, v6
	v_and_b32_e32 v16, 0x70, v3
	v_ashrrev_i32_e32 v3, 3, v2
	v_ashrrev_i32_e32 v8, 3, v8
	v_mul_lo_u32 v9, v14, s4
	v_mad_u64_u32 v[10:11], s[4:5], v3, s25, v[16:17]
	v_mad_u64_u32 v[12:13], s[4:5], v8, s25, v[16:17]
	s_mul_i32 s4, s68, 0x58000
	v_lshl_add_u32 v6, v6, 4, v9
	s_mul_hi_u32 s5, s68, 0x58000
	s_add_u32 s4, s10, s4
	v_lshl_or_b32 v2, v8, 16, v16
	s_addc_u32 s5, s11, s5
	s_lshl_b64 s[6:7], s[68:69], 7
	v_mad_u64_u32 v[8:9], s[36:37], v7, s21, v[4:5]
	v_mad_u64_u32 v[14:15], s[36:37], v14, s21, v[6:7]
	global_load_dwordx4 v[114:117], v8, s[4:5] offset:1024
	global_load_dwordx4 v[118:121], v14, s[4:5] offset:1024
	s_add_u32 s4, s12, s6
	s_addc_u32 s5, s13, s7
	v_lshl_or_b32 v16, v3, 16, v16
	global_load_dwordx4 v[122:125], v16, s[4:5]
	global_load_dwordx4 v[126:129], v2, s[4:5]
	s_waitcnt vmcnt(8)
	s_nop 1
	v_mov_b32_dpp v151, v150 quad_perm:[1,0,3,2] row_mask:0xf bank_mask:0xf
	v_max_f32_e32 v150, v150, v150
	s_waitcnt lgkmcnt(0)
	v_max_f32_e32 v151, v151, v151
	v_max_f32_e32 v150, v150, v151
	s_nop 1
	v_mov_b32_dpp v151, v150 quad_perm:[2,3,0,1] row_mask:0xf bank_mask:0xf
	s_waitcnt lgkmcnt(0)
	v_max_f32_e32 v151, v151, v151
	v_max_f32_e32 v150, v150, v151
	s_nop 1
	v_mov_b32_dpp v151, v150 row_half_mirror row_mask:0xf bank_mask:0xf
	s_waitcnt lgkmcnt(0)
	v_max_f32_e32 v151, v151, v151
	v_max_f32_e32 v150, v150, v151
	s_nop 1
	v_mov_b32_dpp v151, v150 row_mirror row_mask:0xf bank_mask:0xf
	s_waitcnt lgkmcnt(0)
	v_max_f32_e32 v151, v151, v151
	v_max_f32_e32 v151, v150, v151
	s_waitcnt vmcnt(7)
	v_lshlrev_b32_e32 v152, 16, v98
	s_waitcnt vmcnt(6)
; __device__ __forceinline__ float bflo(unsigned w) { return __uint_as_float(w << 16); }
; __device__ __forceinline__ float bfhi(unsigned w) { return __uint_as_float(w & 0xffff0000u); }
; __device__ __forceinline__ float xhalf_sum(float v) { auto rr = __builtin_amdgcn_permlane32_swap(__float_as_uint(v), __float_as_uint(v), false, false); return __uint_as_float(rr[0]) + __uint_as_float(rr[1]); }
; template <int MODE> ...
;     ...
;     if (REV) {
; #pragma unroll
;         for (int d0 = 0; d0 < 4; ++d0) { const u32x4 w = __builtin_bit_cast(u32x4, qr[d0]);
;             qkb += fabsf(pg8::bflo(w.x)) + fabsf(pg8::bfhi(w.x)) + fabsf(pg8::bflo(w.y)) + fabsf(pg8::bfhi(w.y)) + fabsf(pg8::bflo(w.z)) + fabsf(pg8::bfhi(w.z)) + fabsf(pg8::bflo(w.w)) + fabsf(pg8::bfhi(w.w)); }
;         qkb = xhalf_sum(qkb) * kinf * 1.02f;
;     }
;     const int t_lo = MODE == 1 ? (q0 >= 128 ? (q0 - 128) / 64 : 0) : 0, t_hi = (q0 + ROWS) / 64;
;     int kgoff[NKL], kloff[NKL], vgoff[NVL], vloff[NVL];
; #pragma unroll
;     for (int i = 0; i < NKL; ++i) { const int idx = tid + 512 * i, row = idx / KCH, ch = idx % KCH; kgoff[i] = row * N1A + ch * 8; kloff[i] = row * KSTR + ch * 16; }
; #pragma unroll
;     for (int i = 0; i < NVL; ++i) { const int idx = tid + 512 * i, row = idx >> 3, ch = idx & 7; vgoff[i] = row * M + ch * 8; vloff[i] = row * VSTR + ch * 16; }
;     u32x4 kstA[NKL], vstA[NVL], kstB[NKL], vstB[NVL]; float lfA = 0.f, lfB = 0.f, carry = 0.f;
;     ...
;     float mrun = NEG, lsum = 0.f;
;     if (MODE == 1) { mrun = sink2w + sl2w * (float)(wq0 + r32 - q0); lsum = hi == 0 ? 1.f : 0.f; }
;     const bool dovote = (MODE != 0) || (sl2 * (float)(q0 + ROWS) >= 150.0f);
;     const bool fixed = REV && !__any(qkb >= 66.0f);
;     if (MODE == 0 && fixed) mrun = sl2 * (float)(wq0 + r32 - q0) + qkb - 20.0f;
	v_lshlrev_b32_e32 v154, 16, v102
	v_and_b32_e32 v155, 0x7fffffff, v154
	v_and_b32_e32 v154, 0x7fffffff, v152
	v_and_b32_e32 v152, 0xffff0000, v102
	v_and_b32_e32 v156, 0xffff0000, v98
	v_and_b32_e32 v157, 0x7fffffff, v152
	v_and_b32_e32 v156, 0x7fffffff, v156
	v_pk_add_f32 v[154:155], v[154:155], v[156:157]
	v_lshlrev_b32_e32 v152, 16, v99
	v_lshlrev_b32_e32 v156, 16, v103
	v_and_b32_e32 v157, 0x7fffffff, v156
	v_and_b32_e32 v156, 0x7fffffff, v152
	v_pk_add_f32 v[154:155], v[156:157], v[154:155]
	v_and_b32_e32 v152, 0xffff0000, v103
	v_and_b32_e32 v156, 0xffff0000, v99
	v_and_b32_e32 v157, 0x7fffffff, v152
	v_and_b32_e32 v156, 0x7fffffff, v156
	v_pk_add_f32 v[154:155], v[156:157], v[154:155]
	v_lshlrev_b32_e32 v152, 16, v100
	v_lshlrev_b32_e32 v156, 16, v104
	v_and_b32_e32 v157, 0x7fffffff, v156
	v_and_b32_e32 v156, 0x7fffffff, v152
	v_pk_add_f32 v[154:155], v[156:157], v[154:155]
	v_and_b32_e32 v152, 0xffff0000, v104
	v_and_b32_e32 v156, 0xffff0000, v100
	v_and_b32_e32 v157, 0x7fffffff, v152
	v_and_b32_e32 v156, 0x7fffffff, v156
	v_pk_add_f32 v[154:155], v[156:157], v[154:155]
	v_lshlrev_b32_e32 v152, 16, v101
	v_lshlrev_b32_e32 v156, 16, v105
	v_and_b32_e32 v157, 0x7fffffff, v156
	v_and_b32_e32 v156, 0x7fffffff, v152
	v_pk_add_f32 v[154:155], v[156:157], v[154:155]
	v_and_b32_e32 v152, 0xffff0000, v105
	v_and_b32_e32 v156, 0xffff0000, v101
	v_and_b32_e32 v157, 0x7fffffff, v152
	v_and_b32_e32 v156, 0x7fffffff, v156
	v_pk_add_f32 v[154:155], v[156:157], v[154:155]
	s_waitcnt vmcnt(5)
	v_lshlrev_b32_e32 v152, 16, v106
	s_waitcnt vmcnt(4)
	v_lshlrev_b32_e32 v156, 16, v110
	v_and_b32_e32 v157, 0x7fffffff, v156
	v_and_b32_e32 v156, 0x7fffffff, v152
	v_and_b32_e32 v152, 0xffff0000, v110
	v_and_b32_e32 v158, 0xffff0000, v106
	v_and_b32_e32 v159, 0x7fffffff, v152
	v_and_b32_e32 v158, 0x7fffffff, v158
	v_pk_add_f32 v[156:157], v[156:157], v[158:159]
	v_lshlrev_b32_e32 v152, 16, v107
	v_lshlrev_b32_e32 v158, 16, v111
	v_and_b32_e32 v159, 0x7fffffff, v158
	v_and_b32_e32 v158, 0x7fffffff, v152
	v_pk_add_f32 v[156:157], v[158:159], v[156:157]
	v_and_b32_e32 v152, 0xffff0000, v111
	v_and_b32_e32 v158, 0xffff0000, v107
	v_and_b32_e32 v159, 0x7fffffff, v152
	v_and_b32_e32 v158, 0x7fffffff, v158
	v_pk_add_f32 v[156:157], v[158:159], v[156:157]
	v_lshlrev_b32_e32 v152, 16, v108
	v_lshlrev_b32_e32 v158, 16, v112
	v_and_b32_e32 v159, 0x7fffffff, v158
	v_and_b32_e32 v158, 0x7fffffff, v152
	v_pk_add_f32 v[156:157], v[158:159], v[156:157]
	v_and_b32_e32 v152, 0xffff0000, v112
	v_and_b32_e32 v158, 0xffff0000, v108
	v_and_b32_e32 v159, 0x7fffffff, v152
	v_and_b32_e32 v158, 0x7fffffff, v158
	v_pk_add_f32 v[156:157], v[158:159], v[156:157]
	v_lshlrev_b32_e32 v152, 16, v109
	v_lshlrev_b32_e32 v158, 16, v113
	v_and_b32_e32 v159, 0x7fffffff, v158
	v_and_b32_e32 v158, 0x7fffffff, v152
	v_pk_add_f32 v[156:157], v[158:159], v[156:157]
	v_and_b32_e32 v152, 0xffff0000, v113
	v_and_b32_e32 v158, 0xffff0000, v109
	v_and_b32_e32 v159, 0x7fffffff, v152
	v_and_b32_e32 v158, 0x7fffffff, v158
	v_pk_add_f32 v[154:155], v[154:155], v[154:155] op_sel:[0,1] op_sel_hi:[1,0]
	v_pk_add_f32 v[156:157], v[158:159], v[156:157]
	s_nop 0
	v_pk_add_f32 v[154:155], v[154:155], v[156:157]
	s_nop 0
	v_pk_add_f32 v[154:155], v[154:155], v[156:157] op_sel:[0,1] op_sel_hi:[1,0]
	v_mov_b32_e32 v152, v154
	s_nop 1
	v_permlane32_swap_b32_e32 v154, v152
	v_add_f32_e32 v152, v154, v152
	v_mul_f32_e32 v151, v151, v152
	v_mul_f32_e32 v198, 0x3f828f5c, v151
	v_add_u32_e32 v212, 0, v10
	v_add_u32_e32 v214, 0, v12
	s_cmp_lt_u32 s76, 64
	v_cmp_le_f32_e32 vcc, s33, v198
	v_add_u32_e32 v210, 0, v4
	v_add_u32_e32 v211, 0, v6
	v_add_u32_e32 v213, 0x8800, v212
	v_add_u32_e32 v215, 0x8800, v214
	s_cselect_b64 s[4:5], -1, 0
	s_cmp_gt_u32 s76, 63
	s_waitcnt vmcnt(3)
	ds_write_b128 v210, v[114:117]
	s_waitcnt vmcnt(2)
	ds_write_b128 v211, v[118:121]
	s_waitcnt vmcnt(1)
	ds_write2_b64 v213, v[122:123], v[124:125] offset1:1
	s_waitcnt vmcnt(0)
	ds_write2_b64 v215, v[126:127], v[128:129] offset1:1
	s_cbranch_scc1 .LBB0_245
	s_lshl_b32 s6, s68, 6
	s_sub_i32 s6, s6, s70
	v_or_b32_e32 v3, s6, v209
	v_cvt_f32_i32_e32 v3, v3
	v_lshl_add_u32 v4, v209, 2, 0
	v_add_u32_e32 v4, 0x11000, v4
	v_mul_f32_e32 v3, v208, v3
	ds_write_b32 v4, v3

; __device__ __forceinline__ float bflo(unsigned w) { return __uint_as_float(w << 16); }
; __device__ __forceinline__ float bfhi(unsigned w) { return __uint_as_float(w & 0xffff0000u); }
; __device__ __forceinline__ float xhalf_sum(float v) { auto rr = __builtin_amdgcn_permlane32_swap(__float_as_uint(v), __float_as_uint(v), false, false); return __uint_as_float(rr[0]) + __uint_as_float(rr[1]); }
; template <int MODE> ...
;     ...
;     if (REV) {
; #pragma unroll
;         for (int d0 = 0; d0 < 4; ++d0) { const u32x4 w = __builtin_bit_cast(u32x4, qr[d0]);
;             qkb += fabsf(pg8::bflo(w.x)) + fabsf(pg8::bfhi(w.x)) + fabsf(pg8::bflo(w.y)) + fabsf(pg8::bfhi(w.y)) + fabsf(pg8::bflo(w.z)) + fabsf(pg8::bfhi(w.z)) + fabsf(pg8::bflo(w.w)) + fabsf(pg8::bfhi(w.w)); }
;         qkb = xhalf_sum(qkb) * kinf * 1.02f;
;     }
;     const int t_lo = MODE == 1 ? (q0 >= 128 ? (q0 - 128) / 64 : 0) : 0, t_hi = (q0 + ROWS) / 64;
;     int kgoff[NKL], kloff[NKL], vgoff[NVL], vloff[NVL];
; #pragma unroll
;     for (int i = 0; i < NKL; ++i) { const int idx = tid + 512 * i, row = idx / KCH, ch = idx % KCH; kgoff[i] = row * N1A + ch * 8; kloff[i] = row * KSTR + ch * 16; }
; #pragma unroll
;     for (int i = 0; i < NVL; ++i) { const int idx = tid + 512 * i, row = idx >> 3, ch = idx & 7; vgoff[i] = row * M + ch * 8; vloff[i] = row * VSTR + ch * 16; }
;     u32x4 kstA[NKL], vstA[NVL], kstB[NKL], vstB[NVL]; float lfA = 0.f, lfB = 0.f, carry = 0.f;
; __device__ __forceinline__ void attn_phase(LAS unsigned char* lds, const Args& a, int layer, int vcu, int G) {
;     ...
;         int l15_ = threadIdx.x & 15; asm volatile("" : "+v"(l15_)); float kinf = kabs[(b * 16 + l15_) * 11 + 8 + (h >> 2)];
;         _Pragma("unroll") for (int o = 1; o < 16; o <<= 1) kinf = fmaxf(kinf, __shfl_xor(kinf, o));
.Lfox_nolf:
	s_cmp_lt_u32 s2, 64
	s_cselect_b64 s[8:9], -1, 0
	s_cmp_gt_u32 s2, 63
	s_cselect_b64 s[6:7], -1, 0
	v_mov_b32_e32 v137, 0
	s_and_b64 vcc, exec, s[6:7]
	s_waitcnt vmcnt(6)
	s_nop 1
	v_mov_b32_dpp v5, v10 quad_perm:[1,0,3,2] row_mask:0xf bank_mask:0xf
	v_max_f32_e32 v10, v10, v10
	s_waitcnt lgkmcnt(0)
	v_max_f32_e32 v5, v5, v5
	v_max_f32_e32 v5, v10, v5
	s_nop 1
	v_mov_b32_dpp v10, v5 quad_perm:[2,3,0,1] row_mask:0xf bank_mask:0xf
	s_waitcnt lgkmcnt(0)
	v_max_f32_e32 v10, v10, v10
	v_max_f32_e32 v5, v5, v10
	s_nop 1
	v_mov_b32_dpp v20, v5 row_half_mirror row_mask:0xf bank_mask:0xf
	s_waitcnt lgkmcnt(0)
	v_max_f32_e32 v20, v20, v20
	v_max_f32_e32 v5, v5, v20
	s_nop 1
	v_mov_b32_dpp v20, v5 row_mirror row_mask:0xf bank_mask:0xf
	s_waitcnt vmcnt(5)
	v_lshlrev_b32_e32 v10, 16, v66
	s_waitcnt vmcnt(4)
	v_lshlrev_b32_e32 v11, 16, v70
	v_and_b32_e32 v12, 0xffff0000, v70
	v_and_b32_e32 v14, 0xffff0000, v66
	v_lshlrev_b32_e32 v16, 16, v67
	v_lshlrev_b32_e32 v15, 16, v71
	v_and_b32_e32 v11, 0x7fffffff, v11
	v_and_b32_e32 v10, 0x7fffffff, v10
	v_and_b32_e32 v13, 0x7fffffff, v12
	v_and_b32_e32 v12, 0x7fffffff, v14
	v_and_b32_e32 v17, 0xffff0000, v71
	v_and_b32_e32 v18, 0xffff0000, v67
	v_and_b32_e32 v15, 0x7fffffff, v15
	v_and_b32_e32 v14, 0x7fffffff, v16
	v_pk_add_f32 v[10:11], v[10:11], v[12:13]
	v_lshlrev_b32_e32 v21, 16, v68
	v_lshlrev_b32_e32 v19, 16, v72
	v_and_b32_e32 v17, 0x7fffffff, v17
	v_and_b32_e32 v16, 0x7fffffff, v18
	v_pk_add_f32 v[10:11], v[14:15], v[10:11]
	s_waitcnt lgkmcnt(0)
	v_max_f32_e32 v12, v20, v20
	v_and_b32_e32 v19, 0x7fffffff, v19
	v_and_b32_e32 v18, 0x7fffffff, v21
	v_pk_add_f32 v[10:11], v[16:17], v[10:11]
	v_max_f32_e32 v5, v5, v12
	v_and_b32_e32 v12, 0xffff0000, v72
	v_and_b32_e32 v14, 0xffff0000, v68
	v_pk_add_f32 v[10:11], v[18:19], v[10:11]
	v_and_b32_e32 v13, 0x7fffffff, v12
	v_and_b32_e32 v12, 0x7fffffff, v14
	v_pk_add_f32 v[10:11], v[12:13], v[10:11]
	v_lshlrev_b32_e32 v12, 16, v69
	v_lshlrev_b32_e32 v13, 16, v73
	v_and_b32_e32 v13, 0x7fffffff, v13
	v_and_b32_e32 v12, 0x7fffffff, v12
	v_pk_add_f32 v[10:11], v[12:13], v[10:11]
	v_and_b32_e32 v12, 0xffff0000, v73
	v_and_b32_e32 v14, 0xffff0000, v69
	v_and_b32_e32 v13, 0x7fffffff, v12
	v_and_b32_e32 v12, 0x7fffffff, v14
	v_pk_add_f32 v[10:11], v[12:13], v[10:11]
	s_waitcnt vmcnt(3)
	v_lshlrev_b32_e32 v12, 16, v74
	s_waitcnt vmcnt(2)
	v_lshlrev_b32_e32 v13, 16, v78
	v_and_b32_e32 v14, 0xffff0000, v78
	v_and_b32_e32 v16, 0xffff0000, v74
	v_and_b32_e32 v13, 0x7fffffff, v13
	v_and_b32_e32 v12, 0x7fffffff, v12
	v_and_b32_e32 v15, 0x7fffffff, v14
	v_and_b32_e32 v14, 0x7fffffff, v16
	v_pk_add_f32 v[12:13], v[12:13], v[14:15]
	v_lshlrev_b32_e32 v14, 16, v75
	v_lshlrev_b32_e32 v15, 16, v79
	v_and_b32_e32 v15, 0x7fffffff, v15
	v_and_b32_e32 v14, 0x7fffffff, v14
	v_pk_add_f32 v[12:13], v[14:15], v[12:13]
	v_and_b32_e32 v14, 0xffff0000, v79
	v_and_b32_e32 v16, 0xffff0000, v75
	v_and_b32_e32 v15, 0x7fffffff, v14
	v_and_b32_e32 v14, 0x7fffffff, v16
	v_pk_add_f32 v[12:13], v[14:15], v[12:13]
	v_lshlrev_b32_e32 v14, 16, v76
	v_lshlrev_b32_e32 v15, 16, v80
	v_and_b32_e32 v15, 0x7fffffff, v15
	v_and_b32_e32 v14, 0x7fffffff, v14
	v_pk_add_f32 v[12:13], v[14:15], v[12:13]
	v_and_b32_e32 v14, 0xffff0000, v80
	v_and_b32_e32 v16, 0xffff0000, v76
	v_and_b32_e32 v15, 0x7fffffff, v14
	v_and_b32_e32 v14, 0x7fffffff, v16
	v_pk_add_f32 v[12:13], v[14:15], v[12:13]
	v_lshlrev_b32_e32 v14, 16, v77
	v_lshlrev_b32_e32 v15, 16, v81
	v_and_b32_e32 v15, 0x7fffffff, v15
	v_and_b32_e32 v14, 0x7fffffff, v14
	v_pk_add_f32 v[12:13], v[14:15], v[12:13]
	v_and_b32_e32 v14, 0xffff0000, v81
	v_and_b32_e32 v16, 0xffff0000, v77
	v_and_b32_e32 v15, 0x7fffffff, v14
	v_and_b32_e32 v14, 0x7fffffff, v16
	v_pk_add_f32 v[10:11], v[10:11], v[10:11] op_sel:[0,1] op_sel_hi:[1,0]
	v_pk_add_f32 v[12:13], v[14:15], v[12:13]
	s_nop 0
	v_pk_add_f32 v[10:11], v[10:11], v[12:13]
	s_nop 0
	v_pk_add_f32 v[10:11], v[10:11], v[12:13] op_sel:[0,1] op_sel_hi:[1,0]
	s_nop 0
	v_mov_b32_e32 v11, v10
	s_nop 1
	v_permlane32_swap_b32_e32 v10, v11
	v_add_f32_e32 v10, v10, v11
	v_mul_f32_e32 v5, v5, v10
	v_mul_f32_e32 v198, 0x3f828f5c, v5
	v_cmp_le_f32_e64 s[38:39], s33, v198
.LBB0_326:
	v_mad_u64_u32 v[10:11], s[36:37], v9, s25, v[6:7]
	v_add_u32_e32 v135, 0, v10
	v_cndmask_b32_e64 v5, 0, 1, s[8:9]
	v_add_u32_e32 v134, 0, v8
	v_add_u32_e32 v136, 0x8800, v135
	v_cmp_ne_u32_e64 s[36:37], 1, v5
	s_andn2_b64 vcc, exec, s[8:9]
	v_cmp_eq_u32_e64 s[50:51], 63, v3
	v_cmp_gt_u32_e64 s[48:49], 62, v3
	v_cmp_gt_u32_e64 s[46:47], 60, v3
	v_cmp_gt_u32_e64 s[44:45], 56, v3
	v_cmp_gt_u32_e64 s[42:43], 48, v3
	v_cmp_gt_u32_e64 s[40:41], 32, v3
	s_waitcnt vmcnt(1)
	ds_write_b128 v134, v[82:85]
	s_waitcnt vmcnt(0)
	ds_write2_b64 v136, v[86:87], v[88:89] offset1:1
	s_cbranch_vccnz .LBB0_328
	v_mov_b32_e32 v5, v133
	v_lshl_add_u32 v8, v3, 2, 0
	v_add_u32_e32 v8, 0x11000, v8
	v_add_f32_dpp v5, v5, v5 row_shl:1 row_mask:0xf bank_mask:0xf bound_ctrl:0
	s_nop 1
	v_add_f32_dpp v5, v5, v5 row_shl:2 row_mask:0xf bank_mask:0xf bound_ctrl:0
	s_nop 1
	v_add_f32_dpp v5, v5, v5 row_shl:4 row_mask:0xf bank_mask:0xf bound_ctrl:0
	s_nop 1
	v_add_f32_dpp v5, v5, v5 row_shl:8 row_mask:0xf bank_mask:0xf bound_ctrl:0
	v_cmp_gt_u32_e32 vcc, 16, v3
	s_nop 0
	v_readlane_b32 s99, v5, 48
	v_readlane_b32 s100, v5, 32
	v_readlane_b32 s101, v5, 16
	v_mov_b32_e32 v34, 0
	s_nop 0
	v_mov_b32_e32 v35, s99
	v_cndmask_b32_e64 v34, v34, v35, s[42:43]
	v_add_f32_e32 v35, s100, v34
	v_cndmask_b32_e64 v34, v34, v35, s[40:41]
	v_add_f32_e32 v35, s101, v34
	v_cndmask_b32_e32 v34, v34, v35, vcc
	v_add_f32_e32 v5, v5, v34
	s_nop 0
	v_readlane_b32 s99, v5, 0
	v_add_f32_e32 v5, 0, v5
	v_sub_f32_e32 v5, v5, v133
	v_mul_f32_e32 v5, 0x3fb8aa3b, v5
	ds_write_b32 v8, v5
	s_nop 0
	v_mov_b32_e32 v137, s99
